# stick-breaking units: balanced query-chunk assignment between the two workgroup halves (68/68 instead of 72/64 chunk-steps)
# baseline (speedup 1.0000x reference)
; #define LAS __attribute__((address_space(3)))
; #define LDS_BAR() do { asm volatile("s_waitcnt lgkmcnt(0)" ::: "memory"); __builtin_amdgcn_s_barrier(); asm volatile("" ::: "memory"); } while (0)
; #define SB_LOAD(kb_) do { _Pragma("unroll") for (int uu = 0; uu < 2; ++uu) { \
;         pkr[uu] = *(const u32x4*)(P0 + (rowbase + (kb_) * 128 + krow + 64 * uu) * AB_IN + 1536 + 64 * h + 8 * kc8); \
;         pvr[uu] = *(const u32x4*)(P0 + (rowbase + (kb_) * 128 + vs_) * AB_IN + 2048 + 64 * h + 8 * (vc8 + 4 * uu)); } } while (0)
; __device__ __forceinline__ void sb_unit(LAS unsigned char* lds, const bf16_t* P0, bf16_t* MIX, int b, int h, int qc) {
;     ...
;     const size_t rowbase = (size_t)b * SEQ; const int q0 = qc * 128, tq = q0 + 16 * w + fr;
;     const bf16_t* qp = P0 + (rowbase + tq) * AB_IN + 1024 + 64 * h + 8 * fq;
;     const bf16x8 qf0 = *(const bf16x8*)qp, qf1 = *(const bf16x8*)(qp + 32);
;     f32x4 oacc[4];
; #pragma unroll
;     for (int n = 0; n < 4; ++n) oacc[n] = (f32x4){0.f, 0.f, 0.f, 0.f};
;     float R = 1.f;
;     LAS unsigned* flags = (LAS unsigned*)(Vl + 128 * 72);
;     u32x4 pkr[2], pvr[2];
;     const int krow = tid >> 3, kc8 = tid & 7, vs_ = tid & 127, vc8 = tid >> 7;
;     ...
;     SB_LOAD(qc);
;     LDS_BAR();
; __global__ void __launch_bounds__(NTHR, 2) fwd_megakernel(Args a) {
;     ...
;         for (int u = bx; u < 2048 + 1024; u += G) {
;             if (u < 2048) { const int qc = 15 - (u >> 7), bh = u & 127; sb_unit(lds, BIG, MIX, bh >> 3, bh & 7, qc); }
.LBB0_294:
	s_and_b64 vcc, exec, s[0:1]
	s_cbranch_vccz .LBB0_289
	s_ashr_i32 s57, s33, 7
	s_bfe_u32 s0, s57, 0x10001
	s_xor_b32 s57, s57, s0
	s_sub_i32 s0, 15, s57
	s_lshl_b32 s1, s33, 8
	s_lshl_b32 s4, s0, 7
	s_and_b32 s52, s1, 0x7800
	v_add_u32_e32 v91, s4, v89
	v_add_u32_e32 v96, s52, v91
	v_mov_b64_e32 v[8:9], s[26:27]
	v_mad_u64_u32 v[0:1], s[0:1], v96, s3, v[8:9]
	s_lshl_b32 s0, s33, 6
	s_add_i32 s4, s4, s52
	s_and_b32 s53, s0, 0x1c0
	v_or_b32_e32 v10, s4, v84
	s_lshl_b32 s22, s53, 1
	s_waitcnt vmcnt(7)
	v_or_b32_e32 v12, s4, v82
	v_mad_u64_u32 v[10:11], s[0:1], v10, s3, v[8:9]
	v_lshl_add_u64 v[10:11], v[10:11], 0, s[22:23]
	v_mad_u64_u32 v[8:9], s[0:1], v12, s3, v[8:9]
	v_lshlrev_b32_e32 v98, 1, v88
	v_mov_b32_e32 v99, v73
	v_lshl_add_u64 v[10:11], v[10:11], 0, v[98:99]
	s_movk_i32 s0, 0x1000
	v_lshl_add_u64 v[8:9], v[8:9], 0, s[22:23]
	v_lshlrev_b32_e32 v72, 1, v86
	s_waitcnt vmcnt(4)
	v_lshl_add_u64 v[24:25], v[10:11], 0, s[18:19]
	v_add_co_u32_e32 v10, vcc, s0, v10
	v_lshl_add_u64 v[8:9], v[8:9], 0, v[72:73]
	s_nop 0
	v_addc_co_u32_e32 v11, vcc, 0, v11, vcc
	v_lshl_add_u64 v[0:1], v[0:1], 0, s[22:23]
	v_mov_b32_e32 v95, v73
	v_add_co_u32_e32 v16, vcc, 0x50000, v8
	v_lshl_add_u64 v[4:5], v[0:1], 0, v[94:95]
	s_nop 0
	v_addc_co_u32_e32 v17, vcc, 0, v9, vcc
	global_load_dwordx4 v[0:3], v[4:5], off offset:2048
	s_nop 0
	global_load_dwordx4 v[4:7], v[4:5], off offset:2112
	s_nop 0
	v_lshl_add_u64 v[10:11], v[8:9], 0, s[18:19]
	v_lshl_add_u64 v[24:25], v[16:17], 0, s[18:19]
	global_load_dwordx4 v[12:15], v[10:11], off
	s_nop 0
	global_load_dwordx4 v[16:19], v[16:17], off offset:3072
	s_nop 0
	global_load_dwordx4 v[20:23], v[8:9], off offset:3072
	s_nop 0
	global_load_dwordx4 v[24:27], v[24:25], off
	s_waitcnt lgkmcnt(0)
	s_barrier
	s_lshl_b32 s0, s57, 7
	v_mov_b32_e32 v8, 0
	v_mov_b32_e32 v97, v73
	s_sub_i32 s56, 0x780, s0
	s_add_i32 s57, s57, -15
	v_mov_b32_e32 v93, 1.0
	v_mov_b32_e32 v95, 0
	v_mov_b32_e32 v9, v8
	v_mov_b32_e32 v10, v8
	v_mov_b32_e32 v11, v8
	v_mov_b32_e32 v28, v8
	v_mov_b32_e32 v29, v8
	v_mov_b32_e32 v30, v8
	v_mov_b32_e32 v31, v8
	v_mov_b32_e32 v32, v8
	v_mov_b32_e32 v33, v8
	v_mov_b32_e32 v34, v8
	v_mov_b32_e32 v35, v8
	v_mov_b32_e32 v36, v8
	v_mov_b32_e32 v37, v8
	v_mov_b32_e32 v38, v8
	v_mov_b32_e32 v39, v8
	s_branch .LBB0_297
